# f_rows (forget logits): 16 loads per K-iteration issued together with counted waits instead of 32 serialized load-wait-MFMA round trips
# speedup vs baseline: 1.0039x; 1.0039x over previous
.LBB0_540:
	v_lshl_add_u64 v[30:31], v[18:19], 0, v[144:145]
	v_lshl_add_u64 v[26:27], v[16:17], 0, v[144:145]
	v_add_co_u32_e32 v32, vcc, 0x6700000, v26
	s_addk_i32 s33, 0x100
	s_nop 0
	v_addc_co_u32_e32 v33, vcc, 0, v27, vcc
	global_load_dwordx4 v[40:43], v[30:31], off offset:-256
	global_load_dwordx4 v[44:47], v[32:33], off
	global_load_dwordx4 v[48:51], v[30:31], off offset:-192
	global_load_dwordx4 v[52:55], v[32:33], off offset:64
	global_load_dwordx4 v[56:59], v[30:31], off offset:-128
	global_load_dwordx4 v[60:63], v[32:33], off offset:128
	global_load_dwordx4 v[64:67], v[30:31], off offset:-64
	global_load_dwordx4 v[68:71], v[32:33], off offset:192
	global_load_dwordx4 v[72:75], v[30:31], off
	global_load_dwordx4 v[76:79], v[32:33], off offset:256
	global_load_dwordx4 v[80:83], v[30:31], off offset:64
	global_load_dwordx4 v[84:87], v[32:33], off offset:320
	global_load_dwordx4 v[88:91], v[30:31], off offset:128
	global_load_dwordx4 v[92:95], v[32:33], off offset:384
	global_load_dwordx4 v[96:99], v[30:31], off offset:192
	global_load_dwordx4 v[100:103], v[32:33], off offset:448
	v_lshl_add_u64 v[16:17], v[16:17], 0, s[56:57]
	v_lshl_add_u64 v[18:19], v[18:19], 0, s[56:57]
	s_cmpk_gt_u32 s33, 0x3df
	s_waitcnt vmcnt(14)
	v_mfma_f32_16x16x32_bf16 v[0:3], v[40:43], v[44:47], v[0:3]
	s_waitcnt vmcnt(12)
	v_mfma_f32_16x16x32_bf16 v[0:3], v[48:51], v[52:55], v[0:3]
	s_waitcnt vmcnt(10)
	v_mfma_f32_16x16x32_bf16 v[0:3], v[56:59], v[60:63], v[0:3]
	s_waitcnt vmcnt(8)
	v_mfma_f32_16x16x32_bf16 v[0:3], v[64:67], v[68:71], v[0:3]
	s_waitcnt vmcnt(6)
	v_mfma_f32_16x16x32_bf16 v[0:3], v[72:75], v[76:79], v[0:3]
	s_waitcnt vmcnt(4)
	v_mfma_f32_16x16x32_bf16 v[0:3], v[80:83], v[84:87], v[0:3]
	s_waitcnt vmcnt(2)
	v_mfma_f32_16x16x32_bf16 v[0:3], v[88:91], v[92:95], v[0:3]
	s_waitcnt vmcnt(0)
	v_mfma_f32_16x16x32_bf16 v[0:3], v[96:99], v[100:103], v[0:3]
	s_cbranch_scc0 .LBB0_540
	s_and_saveexec_b64 s[42:43], s[38:39]
	s_cbranch_execz .LBB0_538
	v_lshl_or_b32 v16, s30, 4, v4
	v_ashrrev_i32_e32 v17, 31, v16
	v_lshl_add_u64 v[18:19], v[16:17], 4, s[48:49]
	global_load_dwordx4 v[26:29], v[18:19], off
	global_load_dwordx4 v[22:25], v[8:9], off
	v_lshlrev_b64 v[16:17], 5, v[16:17]
	v_lshl_add_u64 v[16:17], v[10:11], 0, v[16:17]
	s_waitcnt vmcnt(1)
	v_mov_b32_e32 v18, v27
	v_mov_b32_e32 v19, v28
	v_mov_b32_e32 v27, v29
	v_pk_add_f32 v[18:19], v[18:19], v[26:27]
	s_nop 0
	v_add_f32_e32 v7, v18, v19
	v_fmamk_f32 v7, v7, 0x3a800000, v184
	v_rsq_f32_e32 v18, v7
	s_waitcnt vmcnt(0)
	v_pk_fma_f32 v[0:1], v[0:1], v[18:19], v[22:23] op_sel_hi:[1,0,1]
	v_pk_fma_f32 v[2:3], v[2:3], v[18:19], v[24:25] op_sel_hi:[1,0,1]
	v_min_f32_e32 v18, 0, v0
	v_mul_f32_e64 v0, |v0|, s46
	v_exp_f32_e32 v0, v0
	v_min_f32_e32 v19, 0, v1
	v_mul_f32_e64 v1, |v1|, s46
	v_exp_f32_e32 v1, v1
	v_add_f32_e32 v0, 1.0, v0
	v_cmp_gt_f32_e32 vcc, s47, v0
	v_min_f32_e32 v22, 0, v2
	v_add_f32_e32 v1, 1.0, v1
	v_cndmask_b32_e64 v7, 0, 32, vcc
	v_ldexp_f32 v0, v0, v7
	v_log_f32_e32 v0, v0
	v_mul_f32_e64 v2, |v2|, s46
	v_exp_f32_e32 v2, v2
	v_min_f32_e32 v23, 0, v3
	v_mul_f32_e32 v7, 0x3f317217, v0
	v_fma_f32 v7, v0, s50, -v7
	v_fmac_f32_e32 v7, 0x3377d1cf, v0
	v_fmac_f32_e32 v7, 0x3f317217, v0
	v_cmp_lt_f32_e64 s[40:41], |v0|, s51
	v_add_f32_e32 v2, 1.0, v2
	v_mul_f32_e64 v3, |v3|, s46
	v_cndmask_b32_e64 v0, v0, v7, s[40:41]
	v_cndmask_b32_e32 v7, 0, v190, vcc
	v_cmp_gt_f32_e32 vcc, s47, v1
	v_sub_f32_e32 v0, v0, v7
	v_exp_f32_e32 v3, v3
	v_cndmask_b32_e64 v7, 0, 32, vcc
	v_ldexp_f32 v1, v1, v7
	v_log_f32_e32 v1, v1
	v_add_f32_e32 v3, 1.0, v3
	v_mul_f32_e32 v7, 0x3f317217, v1
	v_fma_f32 v7, v1, s50, -v7
	v_fmac_f32_e32 v7, 0x3377d1cf, v1
	v_fmac_f32_e32 v7, 0x3f317217, v1
	v_cmp_lt_f32_e64 s[40:41], |v1|, s51
	s_nop 1
	v_cndmask_b32_e64 v1, v1, v7, s[40:41]
	v_cndmask_b32_e32 v7, 0, v190, vcc
	v_cmp_gt_f32_e32 vcc, s47, v2
	v_sub_f32_e32 v1, v1, v7
	v_pk_add_f32 v[0:1], v[18:19], v[0:1] neg_lo:[0,1] neg_hi:[0,1]
	v_cndmask_b32_e64 v7, 0, 32, vcc
	v_ldexp_f32 v2, v2, v7
	v_log_f32_e32 v2, v2
	v_pk_mul_f32 v[0:1], v[0:1], s[54:55] op_sel_hi:[1,0]
	v_mul_f32_e32 v7, 0x3f317217, v2
	v_fma_f32 v7, v2, s50, -v7
	v_fmac_f32_e32 v7, 0x3377d1cf, v2
	v_fmac_f32_e32 v7, 0x3f317217, v2
	v_cmp_lt_f32_e64 s[40:41], |v2|, s51
	s_nop 1
	v_cndmask_b32_e64 v2, v2, v7, s[40:41]
	v_cndmask_b32_e32 v7, 0, v190, vcc
	v_cmp_gt_f32_e32 vcc, s47, v3
	v_sub_f32_e32 v2, v2, v7
	s_nop 0
	v_cndmask_b32_e64 v7, 0, 32, vcc
	v_ldexp_f32 v3, v3, v7
	v_log_f32_e32 v3, v3
	s_nop 0
	v_mul_f32_e32 v7, 0x3f317217, v3
	v_fma_f32 v7, v3, s50, -v7
	v_fmac_f32_e32 v7, 0x3377d1cf, v3
	v_fmac_f32_e32 v7, 0x3f317217, v3
	v_cmp_lt_f32_e64 s[40:41], |v3|, s51
	s_nop 1
	v_cndmask_b32_e64 v3, v3, v7, s[40:41]
	v_cndmask_b32_e32 v7, 0, v190, vcc
	v_sub_f32_e32 v3, v3, v7
	v_pk_add_f32 v[2:3], v[22:23], v[2:3] neg_lo:[0,1] neg_hi:[0,1]
	s_nop 0
	v_pk_mul_f32 v[2:3], v[2:3], s[54:55] op_sel_hi:[1,0]
	global_store_dwordx4 v[16:17], v[0:3], off
	s_branch .LBB0_538
